# InProj epilogue: 8 row-stat loads hoisted, counted vmcnt instead of vmcnt(0) per row
# speedup vs baseline: 1.0096x; 1.0096x over previous
; __device__ __forceinline__ float rstd_of(float ssq) { return __builtin_amdgcn_rsqf(ssq * (1.0f / DM) + EPS); }
;     __device__ __forceinline__ void operator()(const f32x4 (&acc)[2][2][4][2], const Unit& u, int wr, int wc, int fr, int fq) const {
;         const int row0 = u.pm * 256 + wr * 64 + fr, ct = wc * 32 + 8 * fq, pn = u.pn;
;         if (pn < 8) {
;             const int sel = pn >> 1; bf16* base = sel == 0 ? U : sel == 1 ? Q : sel == 2 ? K : V; const float cs = sel == 1 ? C2Q : 1.0f;
;             const int cc = (pn & 1) * 256 + ct;
; #pragma unroll
;             for (int ai = 0; ai < 2; ++ai)
; #pragma unroll
;                 for (int m = 0; m < 4; ++m) { const int r = row0 + ai * 128 + m * 16; const float rs = rstd_of(ssq0[r]) * cs;
;     ...
;                 for (int m = 0; m < 4; ++m) { const int r = row0 + ai * 128 + m * 16; const float rs = rstd_of(ssq0[r]);
.LBB0_237:
	v_lshl_add_u32 v166, s56, 8, v175
	v_or_b32_e32 v164, 16, v166
	v_or_b32_e32 v162, 32, v166
	v_or_b32_e32 v160, 48, v166
	s_mov_b64 s[56:57], -1
	s_cmp_gt_i32 s95, 7
	v_ashrrev_i32_e32 v167, 31, v166
	v_ashrrev_i32_e32 v165, 31, v164
	v_ashrrev_i32_e32 v163, 31, v162
	v_ashrrev_i32_e32 v161, 31, v160
	v_lshl_add_u64 v[226:227], v[166:167], 2, s[14:15]
	global_load_dword v214, v[226:227], off
	global_load_dword v215, v[226:227], off offset:64
	global_load_dword v216, v[226:227], off offset:128
	global_load_dword v217, v[226:227], off offset:192
	global_load_dword v222, v[226:227], off offset:512
	global_load_dword v223, v[226:227], off offset:576
	global_load_dword v224, v[226:227], off offset:640
	global_load_dword v225, v[226:227], off offset:704
	s_cbranch_scc1 .LBB0_240
	s_andn2_b64 vcc, exec, s[56:57]
	s_cbranch_vccz .LBB0_241

; __device__ __forceinline__ unsigned pk2(float lo, float hi) { return pg8::cvt_pk_bf16(lo, hi); }
; __device__ __forceinline__ float fsigmoid(float z) { return __builtin_amdgcn_rcpf(1.0f + __builtin_amdgcn_exp2f(-LOG2E * z)); }
; __device__ __forceinline__ float rstd_of(float ssq) { return __builtin_amdgcn_rsqf(ssq * (1.0f / DM) + EPS); }
;     __device__ __forceinline__ void operator()(const f32x4 (&acc)[2][2][4][2], const Unit& u, int wr, int wc, int fr, int fq) const {
;     ...
;         } else {
;             const int gc = (pn - 8) * 256 + ct;
;             f32x4 bv[2][2];
; #pragma unroll
;             for (int bj = 0; bj < 2; ++bj)
; #pragma unroll
;                 for (int n = 0; n < 2; ++n) bv[bj][n] = *(const f32x4*)(b_gate + gc + bj * 128 + 4 * n);
; #pragma unroll
;             for (int ai = 0; ai < 2; ++ai)
; #pragma unroll
;                 for (int m = 0; m < 4; ++m) { const int r = row0 + ai * 128 + m * 16; const float rs = rstd_of(ssq0[r]);
; #pragma unroll
;                     for (int bj = 0; bj < 2; ++bj) { const f32x4 z0 = acc[ai][bj][m][0] * rs + bv[bj][0], z1 = acc[ai][bj][m][1] * rs + bv[bj][1];
;                         u32x4 w; w.x = pk2(fsigmoid(z0[0]), fsigmoid(z0[1])); w.y = pk2(fsigmoid(z0[2]), fsigmoid(z0[3])); w.z = pk2(fsigmoid(z1[0]), fsigmoid(z1[1])); w.w = pk2(fsigmoid(z1[2]), fsigmoid(z1[3]));
;                         *(u32x4*)(G + (size_t)r * 2048 + gc + bj * 128) = w; } }
.LBB0_240:
	v_lshl_add_u64 v[168:169], v[166:167], 2, s[14:15]
	s_nop 1
	v_lshl_add_u32 v170, s95, 8, v178
	v_ashrrev_i32_e32 v171, 31, v170
	v_lshl_add_u64 v[128:129], v[170:171], 2, s[12:13]
	global_load_dwordx4 v[140:143], v[128:129], off
	global_load_dwordx4 v[136:139], v[128:129], off offset:16
	global_load_dwordx4 v[132:135], v[128:129], off offset:512
	s_nop 0
	global_load_dwordx4 v[128:131], v[128:129], off offset:528
	v_lshlrev_b64 v[172:173], 12, v[166:167]
	v_lshl_add_u64 v[186:187], s[26:27], 0, v[172:173]
	v_lshlrev_b64 v[172:173], 1, v[170:171]
	v_lshl_add_u64 v[170:171], v[186:187], 0, v[172:173]
	v_lshl_add_u64 v[188:189], v[164:165], 2, s[14:15]
	s_mov_b32 s49, 0x80000
	s_mov_b64 s[24:25], 0x80000
	s_waitcnt vmcnt(0)
	v_fmamk_f32 v184, v214, 0x3a800000, v182
	v_rsq_f32_e32 v184, v184
	s_nop 0
	v_pk_fma_f32 v[186:187], v[126:127], v[184:185], v[142:143] op_sel_hi:[1,0,1]
	v_pk_fma_f32 v[190:191], v[124:125], v[184:185], v[140:141] op_sel_hi:[1,0,1]
	v_pk_fma_f32 v[192:193], v[122:123], v[184:185], v[138:139] op_sel_hi:[1,0,1]
	v_pk_fma_f32 v[194:195], v[120:121], v[184:185], v[136:137] op_sel_hi:[1,0,1]
	v_pk_fma_f32 v[196:197], v[118:119], v[184:185], v[134:135] op_sel_hi:[1,0,1]
	v_pk_fma_f32 v[198:199], v[116:117], v[184:185], v[132:133] op_sel_hi:[1,0,1]
	v_pk_fma_f32 v[200:201], v[114:115], v[184:185], v[130:131] op_sel_hi:[1,0,1]
	v_pk_fma_f32 v[184:185], v[112:113], v[184:185], v[128:129] op_sel_hi:[1,0,1]
	v_mul_f32_e32 v186, 0xbfb8aa3b, v186
	v_mul_f32_e32 v187, 0xbfb8aa3b, v187
	v_mul_f32_e32 v190, 0xbfb8aa3b, v190
	v_mul_f32_e32 v191, 0xbfb8aa3b, v191
	v_mul_f32_e32 v194, 0xbfb8aa3b, v194
	v_mul_f32_e32 v195, 0xbfb8aa3b, v195
	v_mul_f32_e32 v192, 0xbfb8aa3b, v192
	v_mul_f32_e32 v193, 0xbfb8aa3b, v193
	v_mul_f32_e32 v184, 0xbfb8aa3b, v184
	v_mul_f32_e32 v185, 0xbfb8aa3b, v185
	v_exp_f32_e32 v186, v186
	v_exp_f32_e32 v187, v187
	v_mul_f32_e32 v198, 0xbfb8aa3b, v198
	v_mul_f32_e32 v199, 0xbfb8aa3b, v199
	v_mul_f32_e32 v196, 0xbfb8aa3b, v196
	v_mul_f32_e32 v197, 0xbfb8aa3b, v197
	v_mul_f32_e32 v200, 0xbfb8aa3b, v200
	v_mul_f32_e32 v201, 0xbfb8aa3b, v201
	v_exp_f32_e32 v190, v190
	v_exp_f32_e32 v191, v191
	v_exp_f32_e32 v194, v194
	v_exp_f32_e32 v195, v195
	v_exp_f32_e32 v192, v192
	v_exp_f32_e32 v193, v193
	v_exp_f32_e32 v184, v184
	v_exp_f32_e32 v185, v185
	v_exp_f32_e32 v198, v198
	v_exp_f32_e32 v199, v199
	v_exp_f32_e32 v196, v196
	v_exp_f32_e32 v197, v197
	v_exp_f32_e32 v200, v200
	v_exp_f32_e32 v201, v201
	v_add_f32_e32 v186, 1.0, v186
	v_add_f32_e32 v187, 1.0, v187
	v_add_f32_e32 v190, 1.0, v190
	v_add_f32_e32 v191, 1.0, v191
	v_add_f32_e32 v194, 1.0, v194
	v_add_f32_e32 v195, 1.0, v195
	v_add_f32_e32 v192, 1.0, v192
	v_add_f32_e32 v193, 1.0, v193
	v_add_f32_e32 v184, 1.0, v184
	v_add_f32_e32 v185, 1.0, v185
	v_rcp_f32_e32 v186, v186
	v_rcp_f32_e32 v187, v187
	v_add_f32_e32 v198, 1.0, v198
	v_add_f32_e32 v199, 1.0, v199
	v_add_f32_e32 v196, 1.0, v196
	v_add_f32_e32 v197, 1.0, v197
	v_add_f32_e32 v200, 1.0, v200
	v_add_f32_e32 v201, 1.0, v201
	v_rcp_f32_e32 v190, v190
	v_rcp_f32_e32 v191, v191
	v_rcp_f32_e32 v194, v194
	v_rcp_f32_e32 v195, v195
	v_rcp_f32_e32 v192, v192
	v_rcp_f32_e32 v193, v193
	v_rcp_f32_e32 v202, v184
	v_rcp_f32_e32 v203, v185
	v_cvt_pk_bf16_f32 v184, v190, v191
	v_cvt_pk_bf16_f32 v185, v186, v187
	v_cvt_pk_bf16_f32 v186, v194, v195
	v_cvt_pk_bf16_f32 v187, v192, v193
	v_rcp_f32_e32 v198, v198
	v_rcp_f32_e32 v199, v199
	v_rcp_f32_e32 v196, v196
	v_rcp_f32_e32 v197, v197
	v_rcp_f32_e32 v200, v200
	v_rcp_f32_e32 v201, v201
	global_store_dwordx4 v[170:171], v[184:187], off
	s_nop 1
	v_cvt_pk_bf16_f32 v184, v198, v199
	v_cvt_pk_bf16_f32 v185, v196, v197
	v_cvt_pk_bf16_f32 v186, v202, v203
	v_cvt_pk_bf16_f32 v187, v200, v201
	global_store_dwordx4 v[170:171], v[184:187], off offset:256
	s_nop 1
	v_lshl_add_u64 v[188:189], v[162:163], 2, s[14:15]
	v_lshlrev_b64 v[184:185], 12, v[164:165]
	v_lshl_add_u64 v[184:185], s[26:27], 0, v[184:185]
	v_lshl_add_u64 v[190:191], v[184:185], 0, v[172:173]
	s_nop 0
	v_fmamk_f32 v186, v215, 0x3a800000, v182
	v_rsq_f32_e32 v186, v186
	s_nop 0
	v_pk_fma_f32 v[184:185], v[110:111], v[186:187], v[142:143] op_sel_hi:[1,0,1]
	v_pk_fma_f32 v[192:193], v[108:109], v[186:187], v[140:141] op_sel_hi:[1,0,1]
	v_pk_fma_f32 v[194:195], v[106:107], v[186:187], v[138:139] op_sel_hi:[1,0,1]
	v_pk_fma_f32 v[196:197], v[104:105], v[186:187], v[136:137] op_sel_hi:[1,0,1]
	v_pk_fma_f32 v[198:199], v[102:103], v[186:187], v[134:135] op_sel_hi:[1,0,1]
	v_pk_fma_f32 v[200:201], v[100:101], v[186:187], v[132:133] op_sel_hi:[1,0,1]
	v_pk_fma_f32 v[202:203], v[98:99], v[186:187], v[130:131] op_sel_hi:[1,0,1]
	v_pk_fma_f32 v[186:187], v[96:97], v[186:187], v[128:129] op_sel_hi:[1,0,1]
	v_mul_f32_e32 v185, 0xbfb8aa3b, v185
	v_mul_f32_e32 v192, 0xbfb8aa3b, v192
	v_mul_f32_e32 v193, 0xbfb8aa3b, v193
	v_mul_f32_e32 v184, 0xbfb8aa3b, v184
	v_mul_f32_e32 v196, 0xbfb8aa3b, v196
	v_mul_f32_e32 v197, 0xbfb8aa3b, v197
	v_mul_f32_e32 v194, 0xbfb8aa3b, v194
	v_mul_f32_e32 v195, 0xbfb8aa3b, v195
	v_mul_f32_e32 v186, 0xbfb8aa3b, v186
	v_mul_f32_e32 v187, 0xbfb8aa3b, v187
	v_exp_f32_e32 v185, v185
	v_mul_f32_e32 v200, 0xbfb8aa3b, v200
	v_mul_f32_e32 v201, 0xbfb8aa3b, v201
	v_mul_f32_e32 v198, 0xbfb8aa3b, v198
	v_mul_f32_e32 v199, 0xbfb8aa3b, v199
	v_mul_f32_e32 v202, 0xbfb8aa3b, v202
	v_mul_f32_e32 v203, 0xbfb8aa3b, v203
	v_exp_f32_e32 v192, v192
	v_exp_f32_e32 v193, v193
	v_exp_f32_e32 v184, v184
	v_exp_f32_e32 v196, v196
	v_exp_f32_e32 v197, v197
	v_exp_f32_e32 v194, v194
	v_exp_f32_e32 v195, v195
	v_exp_f32_e32 v186, v186
	v_exp_f32_e32 v187, v187
	v_exp_f32_e32 v200, v200
	v_exp_f32_e32 v201, v201
; __device__ __forceinline__ unsigned pk2(float lo, float hi) { return pg8::cvt_pk_bf16(lo, hi); }
; __device__ __forceinline__ float fsigmoid(float z) { return __builtin_amdgcn_rcpf(1.0f + __builtin_amdgcn_exp2f(-LOG2E * z)); }
; __device__ __forceinline__ float rstd_of(float ssq) { return __builtin_amdgcn_rsqf(ssq * (1.0f / DM) + EPS); }
;     __device__ __forceinline__ void operator()(const f32x4 (&acc)[2][2][4][2], const Unit& u, int wr, int wc, int fr, int fq) const {
;     ...
;                 for (int m = 0; m < 4; ++m) { const int r = row0 + ai * 128 + m * 16; const float rs = rstd_of(ssq0[r]);
; #pragma unroll
;                     for (int bj = 0; bj < 2; ++bj) { const f32x4 z0 = acc[ai][bj][m][0] * rs + bv[bj][0], z1 = acc[ai][bj][m][1] * rs + bv[bj][1];
;                         u32x4 w; w.x = pk2(fsigmoid(z0[0]), fsigmoid(z0[1])); w.y = pk2(fsigmoid(z0[2]), fsigmoid(z0[3])); w.z = pk2(fsigmoid(z1[0]), fsigmoid(z1[1])); w.w = pk2(fsigmoid(z1[2]), fsigmoid(z1[3]));
;                         *(u32x4*)(G + (size_t)r * 2048 + gc + bj * 128) = w; } }
	v_exp_f32_e32 v198, v198
	v_exp_f32_e32 v199, v199
	v_exp_f32_e32 v202, v202
	v_exp_f32_e32 v203, v203
	v_add_f32_e32 v185, 1.0, v185
	v_add_f32_e32 v192, 1.0, v192
	v_add_f32_e32 v193, 1.0, v193
	v_add_f32_e32 v184, 1.0, v184
	v_add_f32_e32 v196, 1.0, v196
	v_add_f32_e32 v197, 1.0, v197
	v_add_f32_e32 v194, 1.0, v194
	v_add_f32_e32 v195, 1.0, v195
	v_add_f32_e32 v186, 1.0, v186
	v_add_f32_e32 v187, 1.0, v187
	v_rcp_f32_e32 v185, v185
	v_add_f32_e32 v200, 1.0, v200
	v_add_f32_e32 v201, 1.0, v201
	v_add_f32_e32 v198, 1.0, v198
	v_add_f32_e32 v199, 1.0, v199
	v_add_f32_e32 v202, 1.0, v202
	v_add_f32_e32 v203, 1.0, v203
	v_rcp_f32_e32 v192, v192
	v_rcp_f32_e32 v193, v193
	v_rcp_f32_e32 v204, v184
	v_rcp_f32_e32 v196, v196
	v_rcp_f32_e32 v197, v197
	v_rcp_f32_e32 v194, v194
	v_rcp_f32_e32 v195, v195
	v_rcp_f32_e32 v205, v186
	v_rcp_f32_e32 v206, v187
	v_cvt_pk_bf16_f32 v184, v192, v193
	v_cvt_pk_bf16_f32 v185, v204, v185
	v_cvt_pk_bf16_f32 v186, v196, v197
	v_cvt_pk_bf16_f32 v187, v194, v195
	v_rcp_f32_e32 v200, v200
	v_rcp_f32_e32 v201, v201
	v_rcp_f32_e32 v198, v198
	v_rcp_f32_e32 v199, v199
	v_rcp_f32_e32 v202, v202
	v_rcp_f32_e32 v203, v203
	global_store_dwordx4 v[190:191], v[184:187], off
	s_nop 1
	v_cvt_pk_bf16_f32 v184, v200, v201
	v_cvt_pk_bf16_f32 v185, v198, v199
	v_cvt_pk_bf16_f32 v186, v205, v206
	v_cvt_pk_bf16_f32 v187, v202, v203
	global_store_dwordx4 v[190:191], v[184:187], off offset:256
	s_nop 1
	v_lshl_add_u64 v[188:189], v[160:161], 2, s[14:15]
	v_lshlrev_b64 v[184:185], 12, v[162:163]
	v_lshl_add_u64 v[184:185], s[26:27], 0, v[184:185]
	v_lshl_add_u64 v[190:191], v[184:185], 0, v[172:173]
	s_nop 0
	v_fmamk_f32 v186, v216, 0x3a800000, v182
	v_rsq_f32_e32 v186, v186
	s_nop 0
	v_pk_fma_f32 v[184:185], v[94:95], v[186:187], v[142:143] op_sel_hi:[1,0,1]
	v_pk_fma_f32 v[192:193], v[92:93], v[186:187], v[140:141] op_sel_hi:[1,0,1]
	v_pk_fma_f32 v[194:195], v[90:91], v[186:187], v[138:139] op_sel_hi:[1,0,1]
	v_pk_fma_f32 v[196:197], v[88:89], v[186:187], v[136:137] op_sel_hi:[1,0,1]
	v_pk_fma_f32 v[198:199], v[82:83], v[186:187], v[134:135] op_sel_hi:[1,0,1]
	v_pk_fma_f32 v[200:201], v[80:81], v[186:187], v[132:133] op_sel_hi:[1,0,1]
	v_pk_fma_f32 v[202:203], v[78:79], v[186:187], v[130:131] op_sel_hi:[1,0,1]
	v_pk_fma_f32 v[186:187], v[76:77], v[186:187], v[128:129] op_sel_hi:[1,0,1]
	v_mul_f32_e32 v185, 0xbfb8aa3b, v185
	v_mul_f32_e32 v192, 0xbfb8aa3b, v192
	v_mul_f32_e32 v193, 0xbfb8aa3b, v193
	v_mul_f32_e32 v184, 0xbfb8aa3b, v184
	v_mul_f32_e32 v196, 0xbfb8aa3b, v196
	v_mul_f32_e32 v197, 0xbfb8aa3b, v197
	v_mul_f32_e32 v194, 0xbfb8aa3b, v194
	v_mul_f32_e32 v195, 0xbfb8aa3b, v195
	v_mul_f32_e32 v186, 0xbfb8aa3b, v186
	v_mul_f32_e32 v187, 0xbfb8aa3b, v187
	v_exp_f32_e32 v185, v185
	v_mul_f32_e32 v200, 0xbfb8aa3b, v200
	v_mul_f32_e32 v201, 0xbfb8aa3b, v201
	v_mul_f32_e32 v198, 0xbfb8aa3b, v198
	v_mul_f32_e32 v199, 0xbfb8aa3b, v199
	v_mul_f32_e32 v202, 0xbfb8aa3b, v202
	v_mul_f32_e32 v203, 0xbfb8aa3b, v203
	v_exp_f32_e32 v192, v192
	v_exp_f32_e32 v193, v193
	v_exp_f32_e32 v184, v184
	v_exp_f32_e32 v196, v196
	v_exp_f32_e32 v197, v197
	v_exp_f32_e32 v194, v194
	v_exp_f32_e32 v195, v195
	v_exp_f32_e32 v186, v186
	v_exp_f32_e32 v187, v187
	v_exp_f32_e32 v200, v200
	v_exp_f32_e32 v201, v201
	v_exp_f32_e32 v198, v198
	v_exp_f32_e32 v199, v199
	v_exp_f32_e32 v202, v202
	v_exp_f32_e32 v203, v203
	v_add_f32_e32 v185, 1.0, v185
	v_add_f32_e32 v192, 1.0, v192
	v_add_f32_e32 v193, 1.0, v193
	v_add_f32_e32 v184, 1.0, v184
	v_add_f32_e32 v196, 1.0, v196
	v_add_f32_e32 v197, 1.0, v197
	v_add_f32_e32 v194, 1.0, v194
	v_add_f32_e32 v195, 1.0, v195
	v_add_f32_e32 v186, 1.0, v186
	v_add_f32_e32 v187, 1.0, v187
	v_rcp_f32_e32 v185, v185
	v_add_f32_e32 v200, 1.0, v200
	v_add_f32_e32 v201, 1.0, v201
	v_add_f32_e32 v198, 1.0, v198
	v_add_f32_e32 v199, 1.0, v199
	v_add_f32_e32 v202, 1.0, v202
	v_add_f32_e32 v203, 1.0, v203
	v_rcp_f32_e32 v192, v192
	v_rcp_f32_e32 v193, v193
	v_rcp_f32_e32 v204, v184
	v_rcp_f32_e32 v196, v196
	v_rcp_f32_e32 v197, v197
	v_rcp_f32_e32 v194, v194
	v_rcp_f32_e32 v195, v195
	v_rcp_f32_e32 v205, v186
	v_rcp_f32_e32 v206, v187
	v_cvt_pk_bf16_f32 v184, v192, v193
	v_cvt_pk_bf16_f32 v185, v204, v185
	v_cvt_pk_bf16_f32 v186, v196, v197
	v_cvt_pk_bf16_f32 v187, v194, v195
	v_rcp_f32_e32 v200, v200
	v_rcp_f32_e32 v201, v201
	v_rcp_f32_e32 v198, v198
	v_rcp_f32_e32 v199, v199
	v_rcp_f32_e32 v202, v202
	v_rcp_f32_e32 v203, v203
	global_store_dwordx4 v[190:191], v[184:187], off
	s_nop 1
	v_cvt_pk_bf16_f32 v184, v200, v201
	v_cvt_pk_bf16_f32 v185, v198, v199
	v_cvt_pk_bf16_f32 v186, v205, v206
	v_cvt_pk_bf16_f32 v187, v202, v203
	global_store_dwordx4 v[190:191], v[184:187], off offset:256
	s_nop 1
	s_nop 0
	v_lshlrev_b64 v[186:187], 12, v[160:161]
	v_lshl_add_u64 v[186:187], s[26:27], 0, v[186:187]
	v_lshl_add_u64 v[172:173], v[186:187], 0, v[172:173]
	s_nop 0
	v_fmamk_f32 v184, v217, 0x3a800000, v182
	v_rsq_f32_e32 v184, v184
	s_nop 0
	v_pk_fma_f32 v[186:187], v[86:87], v[184:185], v[142:143] op_sel_hi:[1,0,1]
	v_pk_fma_f32 v[188:189], v[84:85], v[184:185], v[140:141] op_sel_hi:[1,0,1]
	v_pk_fma_f32 v[190:191], v[74:75], v[184:185], v[138:139] op_sel_hi:[1,0,1]
	v_pk_fma_f32 v[192:193], v[72:73], v[184:185], v[136:137] op_sel_hi:[1,0,1]
	v_pk_fma_f32 v[194:195], v[70:71], v[184:185], v[134:135] op_sel_hi:[1,0,1]
	v_pk_fma_f32 v[196:197], v[68:69], v[184:185], v[132:133] op_sel_hi:[1,0,1]
	v_pk_fma_f32 v[198:199], v[66:67], v[184:185], v[130:131] op_sel_hi:[1,0,1]
	v_pk_fma_f32 v[184:185], v[64:65], v[184:185], v[128:129] op_sel_hi:[1,0,1]
	v_mul_f32_e32 v186, 0xbfb8aa3b, v186
	v_mul_f32_e32 v187, 0xbfb8aa3b, v187
; __device__ __forceinline__ unsigned pk2(float lo, float hi) { return pg8::cvt_pk_bf16(lo, hi); }
; __device__ __forceinline__ float fsigmoid(float z) { return __builtin_amdgcn_rcpf(1.0f + __builtin_amdgcn_exp2f(-LOG2E * z)); }
; __device__ __forceinline__ float rstd_of(float ssq) { return __builtin_amdgcn_rsqf(ssq * (1.0f / DM) + EPS); }
;     __device__ __forceinline__ void operator()(const f32x4 (&acc)[2][2][4][2], const Unit& u, int wr, int wc, int fr, int fq) const {
;     ...
;                 for (int m = 0; m < 4; ++m) { const int r = row0 + ai * 128 + m * 16; const float rs = rstd_of(ssq0[r]);
; #pragma unroll
;                     for (int bj = 0; bj < 2; ++bj) { const f32x4 z0 = acc[ai][bj][m][0] * rs + bv[bj][0], z1 = acc[ai][bj][m][1] * rs + bv[bj][1];
;                         u32x4 w; w.x = pk2(fsigmoid(z0[0]), fsigmoid(z0[1])); w.y = pk2(fsigmoid(z0[2]), fsigmoid(z0[3])); w.z = pk2(fsigmoid(z1[0]), fsigmoid(z1[1])); w.w = pk2(fsigmoid(z1[2]), fsigmoid(z1[3]));
;                         *(u32x4*)(G + (size_t)r * 2048 + gc + bj * 128) = w; } }
	v_mul_f32_e32 v188, 0xbfb8aa3b, v188
	v_mul_f32_e32 v189, 0xbfb8aa3b, v189
	v_mul_f32_e32 v192, 0xbfb8aa3b, v192
	v_mul_f32_e32 v193, 0xbfb8aa3b, v193
	v_mul_f32_e32 v190, 0xbfb8aa3b, v190
	v_mul_f32_e32 v191, 0xbfb8aa3b, v191
	v_mul_f32_e32 v184, 0xbfb8aa3b, v184
	v_mul_f32_e32 v185, 0xbfb8aa3b, v185
	v_exp_f32_e32 v186, v186
	v_exp_f32_e32 v187, v187
	v_mul_f32_e32 v196, 0xbfb8aa3b, v196
	v_mul_f32_e32 v197, 0xbfb8aa3b, v197
	v_mul_f32_e32 v194, 0xbfb8aa3b, v194
	v_mul_f32_e32 v195, 0xbfb8aa3b, v195
	v_mul_f32_e32 v198, 0xbfb8aa3b, v198
	v_mul_f32_e32 v199, 0xbfb8aa3b, v199
	v_exp_f32_e32 v188, v188
	v_exp_f32_e32 v189, v189
	v_exp_f32_e32 v192, v192
	v_exp_f32_e32 v193, v193
	v_exp_f32_e32 v190, v190
	v_exp_f32_e32 v191, v191
	v_exp_f32_e32 v184, v184
	v_exp_f32_e32 v185, v185
	v_exp_f32_e32 v196, v196
	v_exp_f32_e32 v197, v197
	v_exp_f32_e32 v194, v194
	v_exp_f32_e32 v195, v195
	v_exp_f32_e32 v198, v198
	v_exp_f32_e32 v199, v199
	v_add_f32_e32 v186, 1.0, v186
	v_add_f32_e32 v187, 1.0, v187
	v_add_f32_e32 v188, 1.0, v188
	v_add_f32_e32 v189, 1.0, v189
	v_add_f32_e32 v192, 1.0, v192
	v_add_f32_e32 v193, 1.0, v193
	v_add_f32_e32 v190, 1.0, v190
	v_add_f32_e32 v191, 1.0, v191
	v_add_f32_e32 v184, 1.0, v184
	v_add_f32_e32 v185, 1.0, v185
	v_rcp_f32_e32 v186, v186
	v_rcp_f32_e32 v187, v187
	v_add_f32_e32 v196, 1.0, v196
	v_add_f32_e32 v197, 1.0, v197
	v_add_f32_e32 v194, 1.0, v194
	v_add_f32_e32 v195, 1.0, v195
	v_add_f32_e32 v198, 1.0, v198
	v_add_f32_e32 v199, 1.0, v199
	v_rcp_f32_e32 v188, v188
	v_rcp_f32_e32 v189, v189
	v_rcp_f32_e32 v192, v192
	v_rcp_f32_e32 v193, v193
	v_rcp_f32_e32 v190, v190
	v_rcp_f32_e32 v191, v191
	v_rcp_f32_e32 v200, v184
	v_rcp_f32_e32 v201, v185
	v_cvt_pk_bf16_f32 v184, v188, v189
	v_cvt_pk_bf16_f32 v185, v186, v187
	v_cvt_pk_bf16_f32 v186, v192, v193
	v_cvt_pk_bf16_f32 v187, v190, v191
	v_rcp_f32_e32 v196, v196
	v_rcp_f32_e32 v197, v197
	v_rcp_f32_e32 v194, v194
	v_rcp_f32_e32 v195, v195
	v_rcp_f32_e32 v198, v198
	v_rcp_f32_e32 v199, v199
	global_store_dwordx4 v[172:173], v[184:187], off
	v_add_co_u32_e32 v188, vcc, s49, v170
	s_nop 0
	v_cvt_pk_bf16_f32 v184, v196, v197
	v_cvt_pk_bf16_f32 v185, v194, v195
	v_cvt_pk_bf16_f32 v186, v200, v201
	v_cvt_pk_bf16_f32 v187, v198, v199
	global_store_dwordx4 v[172:173], v[184:187], off offset:256
	s_nop 1
	v_lshl_add_u64 v[172:173], v[170:171], 0, s[24:25]
	v_addc_co_u32_e32 v189, vcc, 0, v171, vcc
	s_mov_b32 s49, 0x90000
	s_mov_b64 s[24:25], 0x90000
	s_nop 0
	v_fmamk_f32 v184, v222, 0x3a800000, v182
	v_rsq_f32_e32 v184, v184
	s_nop 0
	v_pk_fma_f32 v[186:187], v[62:63], v[184:185], v[142:143] op_sel_hi:[1,0,1]
	v_pk_fma_f32 v[190:191], v[60:61], v[184:185], v[140:141] op_sel_hi:[1,0,1]
	v_pk_fma_f32 v[192:193], v[58:59], v[184:185], v[138:139] op_sel_hi:[1,0,1]
	v_pk_fma_f32 v[194:195], v[56:57], v[184:185], v[136:137] op_sel_hi:[1,0,1]
	v_pk_fma_f32 v[196:197], v[54:55], v[184:185], v[134:135] op_sel_hi:[1,0,1]
	v_pk_fma_f32 v[198:199], v[52:53], v[184:185], v[132:133] op_sel_hi:[1,0,1]
	v_pk_fma_f32 v[200:201], v[50:51], v[184:185], v[130:131] op_sel_hi:[1,0,1]
	v_pk_fma_f32 v[184:185], v[48:49], v[184:185], v[128:129] op_sel_hi:[1,0,1]
	v_mul_f32_e32 v186, 0xbfb8aa3b, v186
	v_mul_f32_e32 v187, 0xbfb8aa3b, v187
	v_mul_f32_e32 v190, 0xbfb8aa3b, v190
	v_mul_f32_e32 v191, 0xbfb8aa3b, v191
	v_mul_f32_e32 v194, 0xbfb8aa3b, v194
	v_mul_f32_e32 v195, 0xbfb8aa3b, v195
	v_mul_f32_e32 v192, 0xbfb8aa3b, v192
	v_mul_f32_e32 v193, 0xbfb8aa3b, v193
	v_mul_f32_e32 v184, 0xbfb8aa3b, v184
	v_mul_f32_e32 v185, 0xbfb8aa3b, v185
	v_exp_f32_e32 v186, v186
	v_exp_f32_e32 v187, v187
	v_mul_f32_e32 v198, 0xbfb8aa3b, v198
	v_mul_f32_e32 v199, 0xbfb8aa3b, v199
	v_mul_f32_e32 v196, 0xbfb8aa3b, v196
	v_mul_f32_e32 v197, 0xbfb8aa3b, v197
	v_mul_f32_e32 v200, 0xbfb8aa3b, v200
	v_mul_f32_e32 v201, 0xbfb8aa3b, v201
	v_exp_f32_e32 v190, v190
	v_exp_f32_e32 v191, v191
	v_exp_f32_e32 v194, v194
	v_exp_f32_e32 v195, v195
	v_exp_f32_e32 v192, v192
	v_exp_f32_e32 v193, v193
	v_exp_f32_e32 v184, v184
	v_exp_f32_e32 v185, v185
	v_exp_f32_e32 v198, v198
	v_exp_f32_e32 v199, v199
	v_exp_f32_e32 v196, v196
	v_exp_f32_e32 v197, v197
	v_exp_f32_e32 v200, v200
	v_exp_f32_e32 v201, v201
	v_add_f32_e32 v186, 1.0, v186
	v_add_f32_e32 v187, 1.0, v187
	v_add_f32_e32 v190, 1.0, v190
	v_add_f32_e32 v191, 1.0, v191
	v_add_f32_e32 v194, 1.0, v194
	v_add_f32_e32 v195, 1.0, v195
	v_add_f32_e32 v192, 1.0, v192
	v_add_f32_e32 v193, 1.0, v193
	v_add_f32_e32 v184, 1.0, v184
	v_add_f32_e32 v185, 1.0, v185
	v_rcp_f32_e32 v186, v186
	v_rcp_f32_e32 v187, v187
	v_add_f32_e32 v198, 1.0, v198
	v_add_f32_e32 v199, 1.0, v199
	v_add_f32_e32 v196, 1.0, v196
	v_add_f32_e32 v197, 1.0, v197
	v_add_f32_e32 v200, 1.0, v200
	v_add_f32_e32 v201, 1.0, v201
	v_rcp_f32_e32 v190, v190
	v_rcp_f32_e32 v191, v191
	v_rcp_f32_e32 v194, v194
	v_rcp_f32_e32 v195, v195
	v_rcp_f32_e32 v192, v192
	v_rcp_f32_e32 v193, v193
	v_rcp_f32_e32 v202, v184
	v_rcp_f32_e32 v203, v185
	v_cvt_pk_bf16_f32 v184, v190, v191
	v_cvt_pk_bf16_f32 v185, v186, v187
	v_cvt_pk_bf16_f32 v186, v194, v195
	v_cvt_pk_bf16_f32 v187, v192, v193
	v_rcp_f32_e32 v198, v198
	v_rcp_f32_e32 v199, v199
	v_rcp_f32_e32 v196, v196
	v_rcp_f32_e32 v197, v197
	v_rcp_f32_e32 v200, v200
	v_rcp_f32_e32 v201, v201
	global_store_dwordx4 v[188:189], v[184:187], off
	v_add_co_u32_e32 v188, vcc, s49, v170
	s_nop 0
	v_cvt_pk_bf16_f32 v184, v198, v199
	v_cvt_pk_bf16_f32 v185, v196, v197
	v_cvt_pk_bf16_f32 v186, v202, v203
	v_cvt_pk_bf16_f32 v187, v200, v201
	global_store_dwordx4 v[172:173], v[184:187], off offset:256
	s_nop 1
	v_lshl_add_u64 v[172:173], v[170:171], 0, s[24:25]
	v_addc_co_u32_e32 v189, vcc, 0, v171, vcc
; __device__ __forceinline__ unsigned pk2(float lo, float hi) { return pg8::cvt_pk_bf16(lo, hi); }
; __device__ __forceinline__ float fsigmoid(float z) { return __builtin_amdgcn_rcpf(1.0f + __builtin_amdgcn_exp2f(-LOG2E * z)); }
; __device__ __forceinline__ float rstd_of(float ssq) { return __builtin_amdgcn_rsqf(ssq * (1.0f / DM) + EPS); }
;     __device__ __forceinline__ void operator()(const f32x4 (&acc)[2][2][4][2], const Unit& u, int wr, int wc, int fr, int fq) const {
;     ...
;                 for (int m = 0; m < 4; ++m) { const int r = row0 + ai * 128 + m * 16; const float rs = rstd_of(ssq0[r]);
; #pragma unroll
;                     for (int bj = 0; bj < 2; ++bj) { const f32x4 z0 = acc[ai][bj][m][0] * rs + bv[bj][0], z1 = acc[ai][bj][m][1] * rs + bv[bj][1];
;                         u32x4 w; w.x = pk2(fsigmoid(z0[0]), fsigmoid(z0[1])); w.y = pk2(fsigmoid(z0[2]), fsigmoid(z0[3])); w.z = pk2(fsigmoid(z1[0]), fsigmoid(z1[1])); w.w = pk2(fsigmoid(z1[2]), fsigmoid(z1[3]));
;                         *(u32x4*)(G + (size_t)r * 2048 + gc + bj * 128) = w; } }
	s_mov_b32 s49, 0xa0000
	s_mov_b64 s[24:25], 0xa0000
	s_nop 0
	v_fmamk_f32 v184, v223, 0x3a800000, v182
	v_rsq_f32_e32 v184, v184
	s_nop 0
	v_pk_fma_f32 v[186:187], v[46:47], v[184:185], v[142:143] op_sel_hi:[1,0,1]
	v_pk_fma_f32 v[190:191], v[44:45], v[184:185], v[140:141] op_sel_hi:[1,0,1]
	v_pk_fma_f32 v[192:193], v[42:43], v[184:185], v[138:139] op_sel_hi:[1,0,1]
	v_pk_fma_f32 v[194:195], v[40:41], v[184:185], v[136:137] op_sel_hi:[1,0,1]
	v_pk_fma_f32 v[196:197], v[38:39], v[184:185], v[134:135] op_sel_hi:[1,0,1]
	v_pk_fma_f32 v[198:199], v[36:37], v[184:185], v[132:133] op_sel_hi:[1,0,1]
	v_pk_fma_f32 v[200:201], v[34:35], v[184:185], v[130:131] op_sel_hi:[1,0,1]
	v_pk_fma_f32 v[184:185], v[32:33], v[184:185], v[128:129] op_sel_hi:[1,0,1]
	v_mul_f32_e32 v186, 0xbfb8aa3b, v186
	v_mul_f32_e32 v187, 0xbfb8aa3b, v187
	v_mul_f32_e32 v190, 0xbfb8aa3b, v190
	v_mul_f32_e32 v191, 0xbfb8aa3b, v191
	v_mul_f32_e32 v194, 0xbfb8aa3b, v194
	v_mul_f32_e32 v195, 0xbfb8aa3b, v195
	v_mul_f32_e32 v192, 0xbfb8aa3b, v192
	v_mul_f32_e32 v193, 0xbfb8aa3b, v193
	v_mul_f32_e32 v184, 0xbfb8aa3b, v184
	v_mul_f32_e32 v185, 0xbfb8aa3b, v185
	v_exp_f32_e32 v186, v186
	v_exp_f32_e32 v187, v187
	v_mul_f32_e32 v198, 0xbfb8aa3b, v198
	v_mul_f32_e32 v199, 0xbfb8aa3b, v199
	v_mul_f32_e32 v196, 0xbfb8aa3b, v196
	v_mul_f32_e32 v197, 0xbfb8aa3b, v197
	v_mul_f32_e32 v200, 0xbfb8aa3b, v200
	v_mul_f32_e32 v201, 0xbfb8aa3b, v201
	v_exp_f32_e32 v190, v190
	v_exp_f32_e32 v191, v191
	v_exp_f32_e32 v194, v194
	v_exp_f32_e32 v195, v195
	v_exp_f32_e32 v192, v192
	v_exp_f32_e32 v193, v193
	v_exp_f32_e32 v184, v184
	v_exp_f32_e32 v185, v185
	v_exp_f32_e32 v198, v198
	v_exp_f32_e32 v199, v199
	v_exp_f32_e32 v196, v196
	v_exp_f32_e32 v197, v197
	v_exp_f32_e32 v200, v200
	v_exp_f32_e32 v201, v201
	v_add_f32_e32 v186, 1.0, v186
	v_add_f32_e32 v187, 1.0, v187
	v_add_f32_e32 v190, 1.0, v190
	v_add_f32_e32 v191, 1.0, v191
	v_add_f32_e32 v194, 1.0, v194
	v_add_f32_e32 v195, 1.0, v195
	v_add_f32_e32 v192, 1.0, v192
	v_add_f32_e32 v193, 1.0, v193
	v_add_f32_e32 v184, 1.0, v184
	v_add_f32_e32 v185, 1.0, v185
	v_rcp_f32_e32 v186, v186
	v_rcp_f32_e32 v187, v187
	v_add_f32_e32 v198, 1.0, v198
	v_add_f32_e32 v199, 1.0, v199
	v_add_f32_e32 v196, 1.0, v196
	v_add_f32_e32 v197, 1.0, v197
	v_add_f32_e32 v200, 1.0, v200
	v_add_f32_e32 v201, 1.0, v201
	v_rcp_f32_e32 v190, v190
	v_rcp_f32_e32 v191, v191
	v_rcp_f32_e32 v194, v194
	v_rcp_f32_e32 v195, v195
	v_rcp_f32_e32 v192, v192
	v_rcp_f32_e32 v193, v193
	v_rcp_f32_e32 v202, v184
	v_rcp_f32_e32 v203, v185
	v_cvt_pk_bf16_f32 v184, v190, v191
	v_cvt_pk_bf16_f32 v185, v186, v187
	v_cvt_pk_bf16_f32 v186, v194, v195
	v_cvt_pk_bf16_f32 v187, v192, v193
	v_rcp_f32_e32 v198, v198
	v_rcp_f32_e32 v199, v199
	v_rcp_f32_e32 v196, v196
	v_rcp_f32_e32 v197, v197
	v_rcp_f32_e32 v200, v200
	v_rcp_f32_e32 v201, v201
	global_store_dwordx4 v[188:189], v[184:187], off
	v_add_co_u32_e32 v188, vcc, s49, v170
	s_nop 0
	v_cvt_pk_bf16_f32 v184, v198, v199
	v_cvt_pk_bf16_f32 v185, v196, v197
	v_cvt_pk_bf16_f32 v186, v202, v203
	v_cvt_pk_bf16_f32 v187, v200, v201
	global_store_dwordx4 v[172:173], v[184:187], off offset:256
	s_nop 1
	v_lshl_add_u64 v[172:173], v[170:171], 0, s[24:25]
	v_addc_co_u32_e32 v189, vcc, 0, v171, vcc
	s_mov_b64 s[24:25], 0xb0000
	s_nop 0
	v_fmamk_f32 v184, v224, 0x3a800000, v182
	v_rsq_f32_e32 v184, v184
	s_nop 0
	v_pk_fma_f32 v[186:187], v[30:31], v[184:185], v[142:143] op_sel_hi:[1,0,1]
	v_pk_fma_f32 v[190:191], v[28:29], v[184:185], v[140:141] op_sel_hi:[1,0,1]
	v_pk_fma_f32 v[192:193], v[26:27], v[184:185], v[138:139] op_sel_hi:[1,0,1]
	v_pk_fma_f32 v[194:195], v[24:25], v[184:185], v[136:137] op_sel_hi:[1,0,1]
	v_pk_fma_f32 v[196:197], v[22:23], v[184:185], v[134:135] op_sel_hi:[1,0,1]
	v_pk_fma_f32 v[198:199], v[20:21], v[184:185], v[132:133] op_sel_hi:[1,0,1]
	v_pk_fma_f32 v[200:201], v[18:19], v[184:185], v[130:131] op_sel_hi:[1,0,1]
	v_pk_fma_f32 v[184:185], v[16:17], v[184:185], v[128:129] op_sel_hi:[1,0,1]
	v_mul_f32_e32 v186, 0xbfb8aa3b, v186
	v_mul_f32_e32 v187, 0xbfb8aa3b, v187
	v_mul_f32_e32 v190, 0xbfb8aa3b, v190
	v_mul_f32_e32 v191, 0xbfb8aa3b, v191
	v_mul_f32_e32 v194, 0xbfb8aa3b, v194
	v_mul_f32_e32 v195, 0xbfb8aa3b, v195
	v_mul_f32_e32 v192, 0xbfb8aa3b, v192
	v_mul_f32_e32 v193, 0xbfb8aa3b, v193
	v_mul_f32_e32 v184, 0xbfb8aa3b, v184
	v_mul_f32_e32 v185, 0xbfb8aa3b, v185
	v_exp_f32_e32 v186, v186
	v_exp_f32_e32 v187, v187
	v_mul_f32_e32 v198, 0xbfb8aa3b, v198
	v_mul_f32_e32 v199, 0xbfb8aa3b, v199
	v_mul_f32_e32 v196, 0xbfb8aa3b, v196
	v_mul_f32_e32 v197, 0xbfb8aa3b, v197
	v_mul_f32_e32 v200, 0xbfb8aa3b, v200
	v_mul_f32_e32 v201, 0xbfb8aa3b, v201
	v_exp_f32_e32 v190, v190
	v_exp_f32_e32 v191, v191
	v_exp_f32_e32 v194, v194
	v_exp_f32_e32 v195, v195
; __device__ __forceinline__ unsigned pk2(float lo, float hi) { return pg8::cvt_pk_bf16(lo, hi); }
; __device__ __forceinline__ float fsigmoid(float z) { return __builtin_amdgcn_rcpf(1.0f + __builtin_amdgcn_exp2f(-LOG2E * z)); }
; __device__ __forceinline__ float rstd_of(float ssq) { return __builtin_amdgcn_rsqf(ssq * (1.0f / DM) + EPS); }
;     __device__ __forceinline__ void operator()(const f32x4 (&acc)[2][2][4][2], const Unit& u, int wr, int wc, int fr, int fq) const {
;     ...
;                 for (int m = 0; m < 4; ++m) { const int r = row0 + ai * 128 + m * 16; const float rs = rstd_of(ssq0[r]);
; #pragma unroll
;                     for (int bj = 0; bj < 2; ++bj) { const f32x4 z0 = acc[ai][bj][m][0] * rs + bv[bj][0], z1 = acc[ai][bj][m][1] * rs + bv[bj][1];
;                         u32x4 w; w.x = pk2(fsigmoid(z0[0]), fsigmoid(z0[1])); w.y = pk2(fsigmoid(z0[2]), fsigmoid(z0[3])); w.z = pk2(fsigmoid(z1[0]), fsigmoid(z1[1])); w.w = pk2(fsigmoid(z1[2]), fsigmoid(z1[3]));
;                         *(u32x4*)(G + (size_t)r * 2048 + gc + bj * 128) = w; } }
	v_exp_f32_e32 v192, v192
	v_exp_f32_e32 v193, v193
	v_exp_f32_e32 v184, v184
	v_exp_f32_e32 v185, v185
	v_exp_f32_e32 v198, v198
	v_exp_f32_e32 v199, v199
	v_exp_f32_e32 v196, v196
	v_exp_f32_e32 v197, v197
	v_exp_f32_e32 v200, v200
	v_exp_f32_e32 v201, v201
	v_add_f32_e32 v186, 1.0, v186
	v_add_f32_e32 v187, 1.0, v187
	v_add_f32_e32 v190, 1.0, v190
	v_add_f32_e32 v191, 1.0, v191
	v_add_f32_e32 v194, 1.0, v194
	v_add_f32_e32 v195, 1.0, v195
	v_add_f32_e32 v192, 1.0, v192
	v_add_f32_e32 v193, 1.0, v193
	v_add_f32_e32 v184, 1.0, v184
	v_add_f32_e32 v185, 1.0, v185
	v_rcp_f32_e32 v186, v186
	v_rcp_f32_e32 v187, v187
	v_add_f32_e32 v198, 1.0, v198
	v_add_f32_e32 v199, 1.0, v199
	v_add_f32_e32 v196, 1.0, v196
	v_add_f32_e32 v197, 1.0, v197
	v_add_f32_e32 v200, 1.0, v200
	v_add_f32_e32 v201, 1.0, v201
	v_rcp_f32_e32 v190, v190
	v_rcp_f32_e32 v191, v191
	v_rcp_f32_e32 v194, v194
	v_rcp_f32_e32 v195, v195
	v_rcp_f32_e32 v192, v192
	v_rcp_f32_e32 v193, v193
	v_rcp_f32_e32 v202, v184
	v_rcp_f32_e32 v203, v185
	v_cvt_pk_bf16_f32 v184, v190, v191
	v_cvt_pk_bf16_f32 v185, v186, v187
	v_cvt_pk_bf16_f32 v186, v194, v195
	v_cvt_pk_bf16_f32 v187, v192, v193
	v_rcp_f32_e32 v198, v198
	v_rcp_f32_e32 v199, v199
	v_rcp_f32_e32 v196, v196
	v_rcp_f32_e32 v197, v197
	v_rcp_f32_e32 v200, v200
	v_rcp_f32_e32 v201, v201
	global_store_dwordx4 v[188:189], v[184:187], off
	s_nop 1
	v_cvt_pk_bf16_f32 v184, v198, v199
	v_cvt_pk_bf16_f32 v185, v196, v197
	v_cvt_pk_bf16_f32 v186, v202, v203
	v_cvt_pk_bf16_f32 v187, v200, v201
	global_store_dwordx4 v[172:173], v[184:187], off offset:256
	s_nop 1
	v_lshl_add_u64 v[168:169], v[170:171], 0, s[24:25]
	v_add_co_u32_e32 v170, vcc, s90, v170
	s_nop 0
	v_fmamk_f32 v172, v225, 0x3a800000, v182
	v_rsq_f32_e32 v172, v172
	v_addc_co_u32_e32 v171, vcc, 0, v171, vcc
	v_pk_fma_f32 v[142:143], v[14:15], v[172:173], v[142:143] op_sel_hi:[1,0,1]
	v_pk_fma_f32 v[140:141], v[12:13], v[172:173], v[140:141] op_sel_hi:[1,0,1]
	v_pk_fma_f32 v[138:139], v[10:11], v[172:173], v[138:139] op_sel_hi:[1,0,1]
	v_pk_fma_f32 v[136:137], v[8:9], v[172:173], v[136:137] op_sel_hi:[1,0,1]
	v_pk_fma_f32 v[130:131], v[2:3], v[172:173], v[130:131] op_sel_hi:[1,0,1]
	v_pk_fma_f32 v[128:129], v[0:1], v[172:173], v[128:129] op_sel_hi:[1,0,1]
	v_pk_fma_f32 v[134:135], v[6:7], v[172:173], v[134:135] op_sel_hi:[1,0,1]
	v_pk_fma_f32 v[132:133], v[4:5], v[172:173], v[132:133] op_sel_hi:[1,0,1]
	v_mul_f32_e32 v140, 0xbfb8aa3b, v140
	v_mul_f32_e32 v141, 0xbfb8aa3b, v141
	v_mul_f32_e32 v142, 0xbfb8aa3b, v142
	v_mul_f32_e32 v143, 0xbfb8aa3b, v143
	v_mul_f32_e32 v136, 0xbfb8aa3b, v136
	v_mul_f32_e32 v137, 0xbfb8aa3b, v137
	v_mul_f32_e32 v138, 0xbfb8aa3b, v138
	v_mul_f32_e32 v139, 0xbfb8aa3b, v139
	v_mul_f32_e32 v128, 0xbfb8aa3b, v128
	v_mul_f32_e32 v129, 0xbfb8aa3b, v129
	v_mul_f32_e32 v130, 0xbfb8aa3b, v130
	v_mul_f32_e32 v131, 0xbfb8aa3b, v131
	v_mul_f32_e32 v132, 0xbfb8aa3b, v132
	v_mul_f32_e32 v133, 0xbfb8aa3b, v133
	v_mul_f32_e32 v134, 0xbfb8aa3b, v134
	v_mul_f32_e32 v135, 0xbfb8aa3b, v135
	v_exp_f32_e32 v140, v140
	v_exp_f32_e32 v141, v141
	v_exp_f32_e32 v142, v142
	v_exp_f32_e32 v143, v143
	v_exp_f32_e32 v136, v136
	v_exp_f32_e32 v137, v137
	v_exp_f32_e32 v138, v138
	v_exp_f32_e32 v139, v139
	v_exp_f32_e32 v128, v128
	v_exp_f32_e32 v129, v129
	v_exp_f32_e32 v130, v130
	v_exp_f32_e32 v131, v131
	v_exp_f32_e32 v132, v132
	v_exp_f32_e32 v133, v133
	v_exp_f32_e32 v134, v134
	v_exp_f32_e32 v135, v135
	v_add_f32_e32 v140, 1.0, v140
	v_add_f32_e32 v141, 1.0, v141
	v_add_f32_e32 v142, 1.0, v142
	v_add_f32_e32 v143, 1.0, v143
	v_add_f32_e32 v136, 1.0, v136
	v_add_f32_e32 v137, 1.0, v137
	v_add_f32_e32 v138, 1.0, v138
	v_add_f32_e32 v139, 1.0, v139
	v_add_f32_e32 v128, 1.0, v128
	v_add_f32_e32 v129, 1.0, v129
	v_add_f32_e32 v130, 1.0, v130
	v_add_f32_e32 v131, 1.0, v131
	v_add_f32_e32 v132, 1.0, v132
	v_add_f32_e32 v133, 1.0, v133
	v_add_f32_e32 v134, 1.0, v134
	v_add_f32_e32 v135, 1.0, v135
	v_rcp_f32_e32 v140, v140
	v_rcp_f32_e32 v141, v141
	v_rcp_f32_e32 v142, v142
	v_rcp_f32_e32 v143, v143
	v_rcp_f32_e32 v136, v136
	v_rcp_f32_e32 v137, v137
	v_rcp_f32_e32 v138, v138
	v_rcp_f32_e32 v139, v139
	v_rcp_f32_e32 v172, v128
	v_rcp_f32_e32 v173, v129
	v_rcp_f32_e32 v184, v130
	v_rcp_f32_e32 v185, v131
	v_cvt_pk_bf16_f32 v128, v140, v141
	v_cvt_pk_bf16_f32 v129, v142, v143
	v_cvt_pk_bf16_f32 v130, v136, v137
	v_cvt_pk_bf16_f32 v131, v138, v139
	v_rcp_f32_e32 v132, v132
	v_rcp_f32_e32 v133, v133
	v_rcp_f32_e32 v134, v134
	v_rcp_f32_e32 v135, v135
	global_store_dwordx4 v[170:171], v[128:131], off
	s_nop 1
	v_cvt_pk_bf16_f32 v128, v132, v133
	v_cvt_pk_bf16_f32 v129, v134, v135
	v_cvt_pk_bf16_f32 v130, v172, v173
	v_cvt_pk_bf16_f32 v131, v184, v185
	s_cbranch_execnz .LBB0_239

; __device__ __forceinline__ unsigned pk2(float lo, float hi) { return pg8::cvt_pk_bf16(lo, hi); }
; __device__ __forceinline__ float rstd_of(float ssq) { return __builtin_amdgcn_rsqf(ssq * (1.0f / DM) + EPS); }
;     __device__ __forceinline__ void operator()(const f32x4 (&acc)[2][2][4][2], const Unit& u, int wr, int wc, int fr, int fq) const {
;     ...
;         if (pn < 8) {
;             const int sel = pn >> 1; bf16* base = sel == 0 ? U : sel == 1 ? Q : sel == 2 ? K : V; const float cs = sel == 1 ? C2Q : 1.0f;
;             const int cc = (pn & 1) * 256 + ct;
; #pragma unroll
;             for (int ai = 0; ai < 2; ++ai)
; #pragma unroll
;                 for (int m = 0; m < 4; ++m) { const int r = row0 + ai * 128 + m * 16; const float rs = rstd_of(ssq0[r]) * cs;
; #pragma unroll
;                     for (int bj = 0; bj < 2; ++bj) { const f32x4 v0 = acc[ai][bj][m][0] * rs, v1 = acc[ai][bj][m][1] * rs;
;                         u32x4 w; w.x = pk2(v0[0], v0[1]); w.y = pk2(v0[2], v0[3]); w.z = pk2(v1[0], v1[1]); w.w = pk2(v1[2], v1[3]);
;                         *(u32x4*)(base + (size_t)r * 512 + cc + bj * 128) = w; } }
.LBB0_250:
	v_lshl_add_u64 v[128:129], v[166:167], 2, s[14:15]
	s_nop 1
	s_cmp_eq_u32 s24, 1
	s_cselect_b64 vcc, -1, 0
	s_lshl_b32 s24, s95, 8
	s_and_b32 s24, s24, 0x100
	v_add_u32_e32 v134, s24, v177
	v_cndmask_b32_e32 v140, 1.0, v183, vcc
	v_lshlrev_b64 v[130:131], 10, v[166:167]
	v_lshl_add_u64 v[132:133], v[164:165], 2, s[14:15]
	s_waitcnt vmcnt(7)
	v_fmamk_f32 v135, v214, 0x3a800000, v182
	v_rsq_f32_e32 v136, v135
	v_ashrrev_i32_e32 v135, 31, v134
	v_lshl_add_u64 v[134:135], v[134:135], 1, s[56:57]
	v_lshl_add_u64 v[130:131], v[134:135], 0, v[130:131]
	v_mul_f32_e32 v136, v140, v136
	v_pk_mul_f32 v[126:127], v[126:127], v[136:137] op_sel_hi:[1,0]
	v_pk_mul_f32 v[124:125], v[124:125], v[136:137] op_sel_hi:[1,0]
	v_pk_mul_f32 v[122:123], v[122:123], v[136:137] op_sel_hi:[1,0]
	v_pk_mul_f32 v[120:121], v[120:121], v[136:137] op_sel_hi:[1,0]
	v_pk_mul_f32 v[118:119], v[118:119], v[136:137] op_sel_hi:[1,0]
	v_pk_mul_f32 v[116:117], v[116:117], v[136:137] op_sel_hi:[1,0]
	v_pk_mul_f32 v[138:139], v[114:115], v[136:137] op_sel_hi:[1,0]
	v_pk_mul_f32 v[136:137], v[112:113], v[136:137] op_sel_hi:[1,0]
	v_cvt_pk_bf16_f32 v112, v124, v125
	v_cvt_pk_bf16_f32 v113, v126, v127
	v_cvt_pk_bf16_f32 v114, v120, v121
	v_cvt_pk_bf16_f32 v115, v122, v123
	global_store_dwordx4 v[130:131], v[112:115], off
	v_lshl_add_u64 v[168:169], v[130:131], 0, s[46:47]
	s_nop 0
	v_cvt_pk_bf16_f32 v112, v116, v117
	v_cvt_pk_bf16_f32 v113, v118, v119
	v_cvt_pk_bf16_f32 v114, v136, v137
	v_cvt_pk_bf16_f32 v115, v138, v139
	global_store_dwordx4 v[130:131], v[112:115], off offset:256
	s_nop 1
	s_nop 0
	v_lshl_add_u64 v[114:115], v[162:163], 2, s[14:15]
	s_waitcnt vmcnt(8)
	v_fmamk_f32 v112, v215, 0x3a800000, v182
	v_rsq_f32_e32 v116, v112
	v_lshlrev_b64 v[112:113], 10, v[164:165]
	v_lshl_add_u64 v[112:113], v[134:135], 0, v[112:113]
	v_mul_f32_e32 v116, v140, v116
	v_pk_mul_f32 v[110:111], v[110:111], v[116:117] op_sel_hi:[1,0]
	v_pk_mul_f32 v[108:109], v[108:109], v[116:117] op_sel_hi:[1,0]
	v_pk_mul_f32 v[106:107], v[106:107], v[116:117] op_sel_hi:[1,0]
	v_pk_mul_f32 v[104:105], v[104:105], v[116:117] op_sel_hi:[1,0]
	v_pk_mul_f32 v[102:103], v[102:103], v[116:117] op_sel_hi:[1,0]
	v_pk_mul_f32 v[100:101], v[100:101], v[116:117] op_sel_hi:[1,0]
	v_pk_mul_f32 v[118:119], v[98:99], v[116:117] op_sel_hi:[1,0]
	v_pk_mul_f32 v[116:117], v[96:97], v[116:117] op_sel_hi:[1,0]
	v_cvt_pk_bf16_f32 v96, v108, v109
	v_cvt_pk_bf16_f32 v97, v110, v111
	v_cvt_pk_bf16_f32 v98, v104, v105
	v_cvt_pk_bf16_f32 v99, v106, v107
	global_store_dwordx4 v[112:113], v[96:99], off
	s_nop 1
	v_cvt_pk_bf16_f32 v96, v100, v101
	v_cvt_pk_bf16_f32 v97, v102, v103
	v_cvt_pk_bf16_f32 v98, v116, v117
	v_cvt_pk_bf16_f32 v99, v118, v119
	global_store_dwordx4 v[112:113], v[96:99], off offset:256
	s_nop 1
	s_nop 0
	v_lshl_add_u64 v[98:99], v[160:161], 2, s[14:15]
	s_waitcnt vmcnt(9)
	v_fmamk_f32 v96, v216, 0x3a800000, v182
	v_rsq_f32_e32 v100, v96
	v_lshlrev_b64 v[96:97], 10, v[162:163]
	v_lshl_add_u64 v[96:97], v[134:135], 0, v[96:97]
	v_mul_f32_e32 v100, v140, v100
	v_pk_mul_f32 v[94:95], v[94:95], v[100:101] op_sel_hi:[1,0]
	v_pk_mul_f32 v[92:93], v[92:93], v[100:101] op_sel_hi:[1,0]
	v_pk_mul_f32 v[90:91], v[90:91], v[100:101] op_sel_hi:[1,0]
	v_pk_mul_f32 v[88:89], v[88:89], v[100:101] op_sel_hi:[1,0]
	v_pk_mul_f32 v[82:83], v[82:83], v[100:101] op_sel_hi:[1,0]
	v_pk_mul_f32 v[80:81], v[80:81], v[100:101] op_sel_hi:[1,0]
	v_pk_mul_f32 v[102:103], v[78:79], v[100:101] op_sel_hi:[1,0]
	v_pk_mul_f32 v[100:101], v[76:77], v[100:101] op_sel_hi:[1,0]
	v_cvt_pk_bf16_f32 v76, v92, v93
	v_cvt_pk_bf16_f32 v77, v94, v95
	v_cvt_pk_bf16_f32 v78, v88, v89
	v_cvt_pk_bf16_f32 v79, v90, v91
	global_store_dwordx4 v[96:97], v[76:79], off
	s_nop 1
	v_cvt_pk_bf16_f32 v76, v80, v81
	v_cvt_pk_bf16_f32 v77, v82, v83
	v_cvt_pk_bf16_f32 v78, v100, v101
	v_cvt_pk_bf16_f32 v79, v102, v103
	global_store_dwordx4 v[96:97], v[76:79], off offset:256
	s_nop 1
	s_waitcnt vmcnt(10)
	v_fmamk_f32 v76, v217, 0x3a800000, v182
	v_rsq_f32_e32 v78, v76
	v_lshlrev_b64 v[76:77], 10, v[160:161]
	v_lshl_add_u64 v[76:77], v[134:135], 0, v[76:77]
	v_mul_f32_e32 v78, v140, v78
	v_pk_mul_f32 v[80:81], v[86:87], v[78:79] op_sel_hi:[1,0]
	v_pk_mul_f32 v[82:83], v[84:85], v[78:79] op_sel_hi:[1,0]
	v_pk_mul_f32 v[74:75], v[74:75], v[78:79] op_sel_hi:[1,0]
	v_pk_mul_f32 v[72:73], v[72:73], v[78:79] op_sel_hi:[1,0]
	v_pk_mul_f32 v[70:71], v[70:71], v[78:79] op_sel_hi:[1,0]
	v_pk_mul_f32 v[68:69], v[68:69], v[78:79] op_sel_hi:[1,0]
	v_pk_mul_f32 v[84:85], v[66:67], v[78:79] op_sel_hi:[1,0]
	v_pk_mul_f32 v[78:79], v[64:65], v[78:79] op_sel_hi:[1,0]
	v_cvt_pk_bf16_f32 v64, v82, v83
	v_cvt_pk_bf16_f32 v65, v80, v81
	v_cvt_pk_bf16_f32 v66, v72, v73
	v_cvt_pk_bf16_f32 v67, v74, v75
	global_store_dwordx4 v[76:77], v[64:67], off
	s_nop 1
	v_cvt_pk_bf16_f32 v64, v68, v69
	v_cvt_pk_bf16_f32 v65, v70, v71
	v_cvt_pk_bf16_f32 v66, v78, v79
	v_cvt_pk_bf16_f32 v67, v84, v85
	global_store_dwordx4 v[76:77], v[64:67], off offset:256
	s_nop 1
	s_nop 0
	v_lshl_add_u64 v[64:65], v[130:131], 0, s[40:41]
	s_waitcnt vmcnt(11)
; __device__ __forceinline__ unsigned pk2(float lo, float hi) { return pg8::cvt_pk_bf16(lo, hi); }
; __device__ __forceinline__ float rstd_of(float ssq) { return __builtin_amdgcn_rsqf(ssq * (1.0f / DM) + EPS); }
;     __device__ __forceinline__ void operator()(const f32x4 (&acc)[2][2][4][2], const Unit& u, int wr, int wc, int fr, int fq) const {
;     ...
;                 for (int m = 0; m < 4; ++m) { const int r = row0 + ai * 128 + m * 16; const float rs = rstd_of(ssq0[r]) * cs;
; #pragma unroll
;                     for (int bj = 0; bj < 2; ++bj) { const f32x4 v0 = acc[ai][bj][m][0] * rs, v1 = acc[ai][bj][m][1] * rs;
;                         u32x4 w; w.x = pk2(v0[0], v0[1]); w.y = pk2(v0[2], v0[3]); w.z = pk2(v1[0], v1[1]); w.w = pk2(v1[2], v1[3]);
;                         *(u32x4*)(base + (size_t)r * 512 + cc + bj * 128) = w; } }
	v_fmamk_f32 v66, v222, 0x3a800000, v182
	v_rsq_f32_e32 v68, v66
	v_add_co_u32_e32 v66, vcc, s91, v130
	v_mul_f32_e32 v68, v140, v68
	s_nop 0
	v_addc_co_u32_e32 v67, vcc, 0, v131, vcc
	v_pk_mul_f32 v[62:63], v[62:63], v[68:69] op_sel_hi:[1,0]
	v_pk_mul_f32 v[60:61], v[60:61], v[68:69] op_sel_hi:[1,0]
	v_pk_mul_f32 v[58:59], v[58:59], v[68:69] op_sel_hi:[1,0]
	v_pk_mul_f32 v[56:57], v[56:57], v[68:69] op_sel_hi:[1,0]
	v_pk_mul_f32 v[54:55], v[54:55], v[68:69] op_sel_hi:[1,0]
	v_pk_mul_f32 v[52:53], v[52:53], v[68:69] op_sel_hi:[1,0]
	v_pk_mul_f32 v[70:71], v[50:51], v[68:69] op_sel_hi:[1,0]
	v_pk_mul_f32 v[68:69], v[48:49], v[68:69] op_sel_hi:[1,0]
	v_cvt_pk_bf16_f32 v48, v60, v61
	v_cvt_pk_bf16_f32 v49, v62, v63
	v_cvt_pk_bf16_f32 v50, v56, v57
	v_cvt_pk_bf16_f32 v51, v58, v59
	global_store_dwordx4 v[66:67], v[48:51], off
	s_nop 1
	v_cvt_pk_bf16_f32 v48, v52, v53
	v_cvt_pk_bf16_f32 v49, v54, v55
	v_cvt_pk_bf16_f32 v50, v68, v69
	v_cvt_pk_bf16_f32 v51, v70, v71
	global_store_dwordx4 v[64:65], v[48:51], off offset:256
	s_nop 1
	s_nop 0
	v_lshl_add_u64 v[48:49], v[130:131], 0, s[42:43]
	s_waitcnt vmcnt(12)
	v_fmamk_f32 v50, v223, 0x3a800000, v182
	v_rsq_f32_e32 v52, v50
	v_add_co_u32_e32 v50, vcc, s92, v130
	v_mul_f32_e32 v52, v140, v52
	s_nop 0
	v_addc_co_u32_e32 v51, vcc, 0, v131, vcc
	v_pk_mul_f32 v[46:47], v[46:47], v[52:53] op_sel_hi:[1,0]
	v_pk_mul_f32 v[44:45], v[44:45], v[52:53] op_sel_hi:[1,0]
	v_pk_mul_f32 v[42:43], v[42:43], v[52:53] op_sel_hi:[1,0]
	v_pk_mul_f32 v[40:41], v[40:41], v[52:53] op_sel_hi:[1,0]
	v_pk_mul_f32 v[38:39], v[38:39], v[52:53] op_sel_hi:[1,0]
	v_pk_mul_f32 v[36:37], v[36:37], v[52:53] op_sel_hi:[1,0]
	v_pk_mul_f32 v[54:55], v[34:35], v[52:53] op_sel_hi:[1,0]
	v_pk_mul_f32 v[52:53], v[32:33], v[52:53] op_sel_hi:[1,0]
	v_cvt_pk_bf16_f32 v32, v44, v45
	v_cvt_pk_bf16_f32 v33, v46, v47
	v_cvt_pk_bf16_f32 v34, v40, v41
	v_cvt_pk_bf16_f32 v35, v42, v43
	global_store_dwordx4 v[50:51], v[32:35], off
	s_nop 1
	v_cvt_pk_bf16_f32 v32, v36, v37
	v_cvt_pk_bf16_f32 v33, v38, v39
	v_cvt_pk_bf16_f32 v34, v52, v53
	v_cvt_pk_bf16_f32 v35, v54, v55
	global_store_dwordx4 v[48:49], v[32:35], off offset:256
	s_nop 1
	s_nop 0
	v_lshl_add_u64 v[32:33], v[130:131], 0, s[44:45]
	s_waitcnt vmcnt(13)
	v_fmamk_f32 v34, v224, 0x3a800000, v182
	v_rsq_f32_e32 v36, v34
	v_add_co_u32_e32 v34, vcc, s93, v130
	v_mul_f32_e32 v36, v140, v36
	s_nop 0
	v_addc_co_u32_e32 v35, vcc, 0, v131, vcc
	v_pk_mul_f32 v[30:31], v[30:31], v[36:37] op_sel_hi:[1,0]
	v_pk_mul_f32 v[28:29], v[28:29], v[36:37] op_sel_hi:[1,0]
	v_pk_mul_f32 v[26:27], v[26:27], v[36:37] op_sel_hi:[1,0]
	v_pk_mul_f32 v[24:25], v[24:25], v[36:37] op_sel_hi:[1,0]
	v_pk_mul_f32 v[22:23], v[22:23], v[36:37] op_sel_hi:[1,0]
	v_pk_mul_f32 v[20:21], v[20:21], v[36:37] op_sel_hi:[1,0]
	v_pk_mul_f32 v[38:39], v[18:19], v[36:37] op_sel_hi:[1,0]
	v_pk_mul_f32 v[36:37], v[16:17], v[36:37] op_sel_hi:[1,0]
	v_cvt_pk_bf16_f32 v16, v28, v29
	v_cvt_pk_bf16_f32 v17, v30, v31
	v_cvt_pk_bf16_f32 v18, v24, v25
	v_cvt_pk_bf16_f32 v19, v26, v27
	global_store_dwordx4 v[34:35], v[16:19], off
	s_nop 1
	v_cvt_pk_bf16_f32 v16, v20, v21
	v_cvt_pk_bf16_f32 v17, v22, v23
	v_cvt_pk_bf16_f32 v18, v36, v37
	v_cvt_pk_bf16_f32 v19, v38, v39
	global_store_dwordx4 v[32:33], v[16:19], off offset:256
	s_nop 1
	s_waitcnt vmcnt(14)
	v_fmamk_f32 v16, v225, 0x3a800000, v182
	v_rsq_f32_e32 v18, v16
	v_add_co_u32_e32 v16, vcc, s94, v130
	v_mul_f32_e32 v18, v140, v18
	s_nop 0
	v_addc_co_u32_e32 v17, vcc, 0, v131, vcc
	v_pk_mul_f32 v[14:15], v[14:15], v[18:19] op_sel_hi:[1,0]
	v_pk_mul_f32 v[12:13], v[12:13], v[18:19] op_sel_hi:[1,0]
	v_pk_mul_f32 v[10:11], v[10:11], v[18:19] op_sel_hi:[1,0]
	v_pk_mul_f32 v[8:9], v[8:9], v[18:19] op_sel_hi:[1,0]
	v_pk_mul_f32 v[6:7], v[6:7], v[18:19] op_sel_hi:[1,0]
	v_pk_mul_f32 v[4:5], v[4:5], v[18:19] op_sel_hi:[1,0]
	v_pk_mul_f32 v[20:21], v[2:3], v[18:19] op_sel_hi:[1,0]
	v_pk_mul_f32 v[18:19], v[0:1], v[18:19] op_sel_hi:[1,0]
	v_cvt_pk_bf16_f32 v0, v12, v13
	v_cvt_pk_bf16_f32 v1, v14, v15
	v_cvt_pk_bf16_f32 v2, v8, v9
	v_cvt_pk_bf16_f32 v3, v10, v11
	global_store_dwordx4 v[16:17], v[0:3], off
	v_cvt_pk_bf16_f32 v128, v4, v5
	v_cvt_pk_bf16_f32 v129, v6, v7
	v_cvt_pk_bf16_f32 v130, v18, v19
	v_cvt_pk_bf16_f32 v131, v20, v21
	s_andn2_b64 vcc, exec, s[8:9]
	s_mov_b64 s[8:9], -1
	global_store_dwordx4 v[168:169], v[128:131], off offset:256
	s_cbranch_vccnz .LBB0_226
